# v105 + attention loop: wave-uniform branch ladder shortened on the common path (barrier inlined at the fall-through, one SALU and one taken branch fewer per half-block)
# speedup vs baseline: 1.0030x; 1.0030x over previous
; #define WAIT_BAR(N) asm volatile("s_waitcnt vmcnt(" #N ") lgkmcnt(0)\n\ts_barrier" ::: "memory")
; #define RESC() do { if (resc) { asm volatile("s_waitcnt lgkmcnt(0)" ::: "memory"); \
;       _Pragma("unroll") for (int d_ = 0; d_ < 2; ++d_) _Pragma("unroll") for (int r = 0; r < 16; ++r) o[d_][r] *= wsf[crow(r, hi)]; } } while (0)
; #define ROT() do { sl_prev = sl_cur; sl_cur = sl_next; sl_next = (sl_next == (NSLOT - 1) * SLOTB) ? 0 : sl_next + SLOTB; } while (0)
; template <int THRL> __device__ __forceinline__ void attn_unit(int b, int h, int qb, const bf16* Q, const bf16* __restrict__ K, const bf16* __restrict__ V, bf16* O, char* shm, bool first, int qb_next, bf16x8& qn0, bf16x8& qn1, bf16x8& qn2, bf16x8& qn3) {
;     ...
;     int t = 1;
;     ...
;     for (; t + 5 < NT; t += 2) {
;         STEP(pB0, pB1, pA0, pA1, t, true, true, true);     WAIT_BAR(2); RESC(); ROT();
;         STEP(pA0, pA1, pB0, pB1, t + 1, true, true, true); WAIT_BAR(2); RESC(); ROT();
.LBB0_304:
	s_waitcnt lgkmcnt(14)
	v_mfma_f32_32x32x16_bf16 v[16:31], v[144:147], v[188:191], v[16:31]
	v_exp_f32_e32 v80, v80
	v_exp_f32_e32 v81, v81
	v_exp_f32_e32 v82, v82
	v_exp_f32_e32 v83, v83
	s_waitcnt lgkmcnt(12)
	v_mfma_f32_32x32x16_bf16 v[0:15], v[144:147], v[184:187], v[0:15]
	v_exp_f32_e32 v84, v84
	v_exp_f32_e32 v85, v85
	v_exp_f32_e32 v86, v86
	v_exp_f32_e32 v87, v87
	v_add_u32_e32 v44, s46, v238
	ds_read_b128 v[184:187], v44
	ds_read_b128 v[176:179], v44 offset:512
	v_add_u32_e32 v45, v239, v245
	v_add_u32_e32 v46, v239, v246
	ds_read_b128 v[152:155], v45
	ds_read_b128 v[148:151], v46
	s_waitcnt lgkmcnt(14)
	v_mfma_f32_32x32x16_bf16 v[16:31], v[140:143], v[48:51], v[16:31]
	v_exp_f32_e32 v88, v88
	v_exp_f32_e32 v89, v89
	v_exp_f32_e32 v90, v90
	v_exp_f32_e32 v91, v91
	ds_read_b128 v[180:183], v44 offset:2048
	ds_read_b128 v[172:175], v44 offset:2560
	s_waitcnt lgkmcnt(14)
	v_mfma_f32_32x32x16_bf16 v[0:15], v[140:143], v[52:55], v[0:15]
	v_exp_f32_e32 v92, v92
	v_exp_f32_e32 v93, v93
	v_exp_f32_e32 v94, v94
	v_exp_f32_e32 v95, v95
	ds_read_b128 v[168:171], v44 offset:4096
	ds_read_b128 v[164:167], v44 offset:4608
	s_waitcnt lgkmcnt(14)
	v_mfma_f32_32x32x16_bf16 v[16:31], v[136:139], v[56:59], v[16:31]
	v_exp_f32_e32 v64, v64
	v_exp_f32_e32 v65, v65
	v_exp_f32_e32 v66, v66
	v_exp_f32_e32 v67, v67
	ds_read_b128 v[160:163], v44 offset:6144
	ds_read_b128 v[156:159], v44 offset:6656
	s_waitcnt lgkmcnt(14)
	v_mfma_f32_32x32x16_bf16 v[0:15], v[136:139], v[32:35], v[0:15]
	v_exp_f32_e32 v68, v68
	v_exp_f32_e32 v69, v69
	v_exp_f32_e32 v70, v70
	v_exp_f32_e32 v71, v71
	s_waitcnt lgkmcnt(12)
	v_mfma_f32_32x32x16_bf16 v[16:31], v[132:135], v[36:39], v[16:31]
	v_exp_f32_e32 v72, v72
	v_exp_f32_e32 v73, v73
	v_exp_f32_e32 v74, v74
	v_exp_f32_e32 v75, v75
	s_waitcnt lgkmcnt(10)
	v_mfma_f32_32x32x16_bf16 v[0:15], v[132:135], v[40:43], v[0:15]
	v_exp_f32_e32 v76, v76
	v_exp_f32_e32 v77, v77
	v_exp_f32_e32 v78, v78
	v_exp_f32_e32 v79, v79
	s_mov_b64 s[62:63], -1
	s_and_b64 vcc, exec, s[60:61]
	s_cbranch_vccnz .LBB0_329
	s_waitcnt vmcnt(2) lgkmcnt(0)
	s_barrier

; #define WAIT_BAR(N) asm volatile("s_waitcnt vmcnt(" #N ") lgkmcnt(0)\n\ts_barrier" ::: "memory")
; #define RESC() do { if (resc) { asm volatile("s_waitcnt lgkmcnt(0)" ::: "memory"); \
;       _Pragma("unroll") for (int d_ = 0; d_ < 2; ++d_) _Pragma("unroll") for (int r = 0; r < 16; ++r) o[d_][r] *= wsf[crow(r, hi)]; } } while (0)
; #define ROT() do { sl_prev = sl_cur; sl_cur = sl_next; sl_next = (sl_next == (NSLOT - 1) * SLOTB) ? 0 : sl_next + SLOTB; } while (0)
; template <int THRL> __device__ __forceinline__ void attn_unit(int b, int h, int qb, const bf16* Q, const bf16* __restrict__ K, const bf16* __restrict__ V, bf16* O, char* shm, bool first, int qb_next, bf16x8& qn0, bf16x8& qn1, bf16x8& qn2, bf16x8& qn3) {
;     ...
;     int t = 1;
;     ...
;     for (; t + 5 < NT; t += 2) {
;         STEP(pB0, pB1, pA0, pA1, t, true, true, true);     WAIT_BAR(2); RESC(); ROT();
;         STEP(pA0, pA1, pB0, pB1, t + 1, true, true, true); WAIT_BAR(2); RESC(); ROT();
.LBB0_323:
	s_waitcnt lgkmcnt(4)
	v_mfma_f32_32x32x16_bf16 v[0:15], v[136:139], v[80:83], v[0:15]
	v_exp_f32_e32 v36, v36
	v_exp_f32_e32 v37, v37
	v_exp_f32_e32 v38, v38
	v_exp_f32_e32 v39, v39
	s_waitcnt lgkmcnt(2)
	v_mfma_f32_32x32x16_bf16 v[16:31], v[132:135], v[68:71], v[16:31]
	v_exp_f32_e32 v40, v40
	v_exp_f32_e32 v41, v41
	v_exp_f32_e32 v42, v42
	v_exp_f32_e32 v43, v43
	s_waitcnt lgkmcnt(0)
	v_mfma_f32_32x32x16_bf16 v[0:15], v[132:135], v[64:67], v[0:15]
	v_exp_f32_e32 v44, v44
	v_exp_f32_e32 v45, v45
	v_exp_f32_e32 v46, v46
	v_exp_f32_e32 v47, v47
	s_mov_b64 s[8:9], -1
	s_and_b64 vcc, exec, s[62:63]
	s_cbranch_vccnz .LBB0_335
	s_waitcnt vmcnt(2) lgkmcnt(0)
	s_barrier
